# P7 gate/groupnorm: fifth trip moved from waves 0..255 to wave 0 of every workgroup
# speedup vs baseline: 1.0068x; 1.0017x over previous
.LBB0_1541:
	s_cmpk_lt_i32 s73, 0x2100
	v_mov_b32_e32 v0, v184
	s_cbranch_scc0 .LBB0_1544
	v_and_b32_e32 v1, 64, v198
	v_add_u32_e32 v1, 64, v1
	v_xor_b32_e32 v3, 1, v198
	v_cmp_lt_i32_e32 vcc, v3, v1
	s_movk_i32 s16, 0x5f
	s_mov_b64 s[66:67], s[54:55]
	v_cndmask_b32_e32 v3, v198, v3, vcc
	v_lshlrev_b32_e32 v80, 2, v3
	v_xor_b32_e32 v3, 2, v198
	v_cmp_lt_i32_e32 vcc, v3, v1
	v_lshlrev_b32_e32 v2, 3, v0
	v_add_u32_e32 v9, 0x6f, v0
	v_cndmask_b32_e32 v3, v198, v3, vcc
	v_lshlrev_b32_e32 v81, 2, v3
	v_xor_b32_e32 v3, 4, v198
	v_cmp_lt_i32_e32 vcc, v3, v1
	s_mov_b64 s[64:65], s[52:53]
	s_mov_b64 s[62:63], s[50:51]
	v_cndmask_b32_e32 v3, v198, v3, vcc
	v_lshlrev_b32_e32 v82, 2, v3
	v_xor_b32_e32 v3, 8, v198
	v_cmp_lt_i32_e32 vcc, v3, v1
	v_readlane_b32 s40, v252, 48
	s_lshl_b32 s38, s73, 1
	v_cndmask_b32_e32 v3, v198, v3, vcc
	v_lshlrev_b32_e32 v83, 2, v3
	v_xor_b32_e32 v3, 16, v198
	v_cmp_lt_i32_e32 vcc, v3, v1
	v_add_u32_e32 v4, 0x200, v2
	v_add_u32_e32 v6, 0x400, v2
	v_cndmask_b32_e32 v3, v198, v3, vcc
	v_lshlrev_b32_e32 v84, 2, v3
	v_xor_b32_e32 v3, 32, v198
	v_cmp_lt_i32_e32 vcc, v3, v1
	v_add_u32_e32 v8, 0xffffffb0, v0
	v_cmp_gt_u32_e64 s[6:7], s16, v9
	v_cndmask_b32_e32 v1, v198, v3, vcc
	v_lshlrev_b32_e32 v85, 2, v1
	v_add_u32_e32 v1, 47, v0
	v_cmp_gt_u32_e64 s[0:1], s16, v1
	v_subrev_u32_e32 v1, 48, v0
	v_cmp_gt_u32_e64 s[2:3], 48, v1
	v_add_u32_e32 v1, 0xffffffa0, v0
	v_cmp_gt_u32_e64 s[4:5], 48, v1
	v_add_u32_e32 v1, 0xffffff70, v0
	v_add_u32_e32 v9, 16, v0
	v_cmp_gt_u32_e64 s[14:15], 48, v1
	v_add_u32_e32 v1, 0xaf, v0
	v_readlane_b32 s42, v252, 50
	v_readlane_b32 s43, v252, 51
	v_readlane_b32 s46, v252, 54
	v_readlane_b32 s47, v252, 55
	v_ashrrev_i32_e32 v3, 31, v2
	v_ashrrev_i32_e32 v5, 31, v4
	v_ashrrev_i32_e32 v7, 31, v6
	v_cmp_gt_u32_e64 s[8:9], 48, v9
	v_subrev_u32_e32 v9, 32, v0
	v_cmp_gt_u32_e64 s[12:13], 48, v8
	v_add_u32_e32 v8, 0x50, v0
	v_cmp_gt_u32_e64 s[16:17], s16, v1
	v_add_u32_e32 v1, 32, v0
	v_add_u32_e32 v0, -16, v0
	s_mov_b64 s[42:43], s[46:47]
	s_ashr_i32 s39, s38, 31
	v_cmp_gt_u32_e64 s[10:11], 48, v9
	v_cmp_gt_u32_e64 s[18:19], 48, v8
	v_cmp_gt_u32_e64 s[20:21], 48, v1
	v_cmp_gt_u32_e64 s[22:23], 48, v0
	v_lshl_add_u64 v[8:9], v[2:3], 2, s[42:43]
	v_lshl_add_u64 v[10:11], v[6:7], 2, s[42:43]
	s_lshl_b64 s[24:25], s[38:39], 12
	v_lshlrev_b64 v[0:1], 1, v[2:3]
	v_lshlrev_b64 v[2:3], 1, v[4:5]
	v_lshlrev_b64 v[4:5], 1, v[6:7]
	v_mov_b32_e32 v6, 0x2600
	v_lshl_add_u64 v[12:13], s[24:25], 0, v[0:1]
	v_lshl_add_u64 v[14:15], s[24:25], 0, v[2:3]
	v_lshl_add_u64 v[16:17], s[24:25], 0, v[4:5]
	v_mad_i64_i32 v[20:21], s[24:25], s38, v6, v[2:3]
	v_mov_b32_e32 v2, 0xc00
	s_lshl_b32 s30, s94, 4
	v_readlane_b32 s52, v252, 60
	v_readlane_b32 s53, v252, 61
	v_readlane_b32 s54, v252, 62
	v_readlane_b32 s55, v252, 63
	v_mad_i64_i32 v[18:19], s[24:25], s38, v6, v[0:1]
	v_mad_i64_i32 v[22:23], s[24:25], s38, v6, v[4:5]
	v_mad_i64_i32 v[24:25], s[24:25], s38, v2, v[0:1]
	v_readlane_b32 s41, v252, 49
	v_readlane_b32 s44, v252, 52
	v_readlane_b32 s45, v252, 53
	v_readlane_b32 s50, v252, 58
	v_readlane_b32 s51, v252, 59
	s_mov_b64 s[52:53], s[64:65]
	s_ashr_i32 s31, s30, 31
	s_mov_b32 s24, 0x358637bd
	s_mov_b64 s[54:55], s[66:67]
	s_mov_b64 s[50:51], s[62:63]
	s_lshl_b64 s[40:41], s[30:31], 12
	s_mul_i32 s42, s94, 0x26000
	s_mul_hi_i32 s43, s30, 0x2600
	s_mul_i32 s44, s94, 0xc000
	s_mul_hi_i32 s45, s30, 0xc00
	s_mov_b32 s46, 0x3b2aaaab
	s_mov_b32 s31, 0x800000
	s_mov_b32 s33, 0xee94000
	s_mov_b32 s39, 0xee95000
	v_mov_b64_e32 v[26:27], s[24:25]
	v_readlane_b32 s48, v252, 56
	v_readlane_b32 s49, v252, 57
	global_load_dwordx4 v[200:203], v[8:9], off
	global_load_dwordx4 v[204:207], v[8:9], off offset:16
	global_load_dwordx4 v[208:211], v[8:9], off offset:2048
	global_load_dwordx4 v[212:215], v[8:9], off offset:2064
	global_load_dwordx4 v[216:219], v[10:11], off
	global_load_dwordx4 v[220:223], v[10:11], off offset:16
	s_mov_b32 s98, 0
	s_lshr_b32 s99, s38, 1
.LBB0_1543:
	v_lshl_add_u64 v[36:37], s[54:55], 0, v[24:25]
	v_add_co_u32_e32 v48, vcc, 0x14114000, v36
	v_lshl_add_u64 v[38:39], s[54:55], 0, v[18:19]
	s_nop 0
	v_addc_co_u32_e32 v49, vcc, 0, v37, vcc
	v_add_co_u32_e32 v62, vcc, 0x51d4000, v38
	v_lshl_add_u64 v[40:41], s[54:55], 0, v[20:21]
	s_nop 0
	v_addc_co_u32_e32 v63, vcc, 0, v39, vcc
	global_load_dwordx4 v[50:53], v[48:49], off offset:1024
	global_load_dwordx4 v[54:57], v[48:49], off
	global_load_dwordx4 v[58:61], v[48:49], off offset:2048
	global_load_dwordx4 v[86:89], v[48:49], off offset:3072
	v_add_co_u32_e32 v48, vcc, 0x51d4000, v40
	v_lshl_add_u64 v[42:43], s[54:55], 0, v[22:23]
	s_nop 0
	v_addc_co_u32_e32 v49, vcc, 0, v41, vcc
	global_load_dwordx4 v[90:93], v[62:63], off offset:1024
	global_load_dwordx4 v[94:97], v[48:49], off offset:1024
	v_add_co_u32_e32 v62, vcc, 0x51d4000, v42
	v_lshl_add_u64 v[46:47], s[54:55], 0, v[12:13]
	s_nop 0
	v_addc_co_u32_e32 v63, vcc, 0, v43, vcc
	v_add_co_u32_e32 v38, vcc, 0x51d6000, v38
	v_add_co_u32_e64 v44, s[24:25], s33, v46
	s_nop 0
	v_addc_co_u32_e32 v39, vcc, 0, v39, vcc
	v_add_co_u32_e32 v36, vcc, 0x14115000, v36
	global_load_dwordx4 v[98:101], v[62:63], off offset:1024
	global_load_dwordx4 v[102:105], v[38:39], off offset:2560
	v_addc_co_u32_e32 v37, vcc, 0, v37, vcc
	v_add_co_u32_e32 v38, vcc, 0x51d6000, v40
	global_load_dwordx4 v[106:109], v[36:37], off
	global_load_dwordx4 v[110:113], v[36:37], off offset:1024
	v_addc_co_u32_e32 v39, vcc, 0, v41, vcc
	v_add_co_u32_e32 v36, vcc, 0x51d6000, v42
	v_lshl_add_u64 v[30:31], s[54:55], 0, v[14:15]
	s_nop 0
	v_addc_co_u32_e32 v37, vcc, 0, v43, vcc
	global_load_dwordx4 v[114:117], v[38:39], off offset:2560
	global_load_dwordx4 v[118:121], v[36:37], off offset:2560
	v_addc_co_u32_e64 v45, s[24:25], 0, v47, s[24:25]
	v_add_co_u32_e64 v34, s[24:25], s33, v30
	v_lshl_add_u64 v[28:29], s[54:55], 0, v[16:17]
	s_nop 0
	v_addc_co_u32_e64 v35, s[24:25], 0, v31, s[24:25]
	v_add_co_u32_e64 v32, s[24:25], s33, v28
	s_add_i32 s98, s98, 1
	s_cmp_lg_u32 s98, 4
	s_cbranch_scc1 .Lgn_a
	s_movk_i32 s30, 0x7fff
	s_and_b32 s100, s99, 7
	s_cmp_lg_u32 s100, 0
	s_cbranch_scc1 .Lgn_a
	s_lshr_b32 s100, s99, 3
	s_mul_i32 s100, s100, 14
	s_sub_i32 s30, 0x1000, s100
	s_lshl_b32 s40, s30, 12
	s_mov_b32 s41, 0
	s_mul_i32 s42, s30, 0x2600
	s_mov_b32 s43, 0
	s_mul_i32 s44, s30, 0xc00
	s_mov_b32 s45, 0
.Lgn_a:
	s_add_i32 s38, s38, s30
	s_nop 0
	v_addc_co_u32_e64 v33, s[24:25], 0, v29, s[24:25]
	v_add_co_u32_e64 v46, s[24:25], s39, v46
	v_lshl_add_u64 v[12:13], v[12:13], 0, s[40:41]
	s_nop 0
	v_addc_co_u32_e64 v47, s[24:25], 0, v47, s[24:25]
	v_lshl_add_u64 v[14:15], v[14:15], 0, s[40:41]
	v_lshl_add_u64 v[16:17], v[16:17], 0, s[40:41]
	v_lshl_add_u64 v[18:19], v[18:19], 0, s[42:43]
	v_lshl_add_u64 v[20:21], v[20:21], 0, s[42:43]
	v_lshl_add_u64 v[22:23], v[22:23], 0, s[42:43]
	v_lshl_add_u64 v[24:25], v[24:25], 0, s[44:45]
	s_cmpk_lt_i32 s38, 0x4200
	s_waitcnt vmcnt(11)
	v_lshlrev_b32_e32 v65, 16, v50
	s_waitcnt vmcnt(10)
	v_lshlrev_b32_e32 v72, 16, v56
	v_and_b32_e32 v74, 0xffff0000, v56
	s_waitcnt vmcnt(8)
	v_lshlrev_b32_e32 v48, 16, v86
	v_and_b32_e32 v36, 0xffff0000, v86
	v_lshlrev_b32_e32 v56, 16, v88
	v_and_b32_e32 v40, 0xffff0000, v88
	v_lshlrev_b32_e32 v64, 16, v54
	v_and_b32_e32 v67, 0xffff0000, v50
	s_waitcnt vmcnt(7)
	v_lshlrev_b32_e32 v86, 16, v90
	v_and_b32_e32 v88, 0xffff0000, v90
	v_and_b32_e32 v122, 0xffff0000, v91
	v_and_b32_e32 v66, 0xffff0000, v54
	v_lshlrev_b32_e32 v69, 16, v51
	v_lshlrev_b32_e32 v68, 16, v55
	v_and_b32_e32 v71, 0xffff0000, v51
	v_and_b32_e32 v70, 0xffff0000, v55
	v_lshlrev_b32_e32 v73, 16, v52
	v_and_b32_e32 v75, 0xffff0000, v52
	v_lshlrev_b32_e32 v50, 16, v58
	v_and_b32_e32 v51, 0xffff0000, v58
	v_and_b32_e32 v54, 0xffff0000, v59
	v_lshlrev_b32_e32 v55, 16, v59
	v_and_b32_e32 v58, 0xffff0000, v60
	v_lshlrev_b32_e32 v59, 16, v60
	v_lshlrev_b32_e32 v52, 16, v87
	v_and_b32_e32 v38, 0xffff0000, v87
	v_lshlrev_b32_e32 v60, 16, v89
	v_and_b32_e32 v42, 0xffff0000, v89
	v_lshlrev_b32_e32 v90, 16, v91
	v_lshlrev_b32_e32 v124, 16, v92
	v_and_b32_e32 v92, 0xffff0000, v92
	v_lshlrev_b32_e32 v126, 16, v93
	v_and_b32_e32 v128, 0xffff0000, v93
	s_waitcnt vmcnt(6)
	v_lshlrev_b32_e32 v87, 16, v94
	v_and_b32_e32 v89, 0xffff0000, v94
	v_mul_f32_e32 v37, 0xbfb8aa3b, v86
	v_mul_f32_e32 v39, 0xbfb8aa3b, v88
	v_mul_f32_e32 v43, 0xbfb8aa3b, v122
	v_lshlrev_b32_e32 v77, 16, v53
	v_lshlrev_b32_e32 v76, 16, v57
	v_and_b32_e32 v79, 0xffff0000, v53
	v_and_b32_e32 v78, 0xffff0000, v57
	v_and_b32_e32 v62, 0xffff0000, v61
	v_lshlrev_b32_e32 v63, 16, v61
	v_lshlrev_b32_e32 v91, 16, v95
	v_mul_f32_e32 v41, 0xbfb8aa3b, v90
	v_and_b32_e32 v123, 0xffff0000, v95
	v_lshlrev_b32_e32 v125, 16, v96
	v_mul_f32_e32 v49, 0xbfb8aa3b, v124
	v_and_b32_e32 v93, 0xffff0000, v96
	v_mul_f32_e32 v53, 0xbfb8aa3b, v92
	v_lshlrev_b32_e32 v127, 16, v97
	v_mul_f32_e32 v57, 0xbfb8aa3b, v126
	v_and_b32_e32 v129, 0xffff0000, v97
	v_mul_f32_e32 v61, 0xbfb8aa3b, v128
	v_exp_f32_e32 v142, v37
	v_exp_f32_e32 v143, v39
	v_exp_f32_e32 v145, v43
	v_mul_f32_e32 v37, 0xbfb8aa3b, v87
	v_mul_f32_e32 v39, 0xbfb8aa3b, v89
	s_waitcnt vmcnt(5)
	v_lshlrev_b32_e32 v94, 16, v98
	v_and_b32_e32 v95, 0xffff0000, v98
	v_exp_f32_e32 v144, v41
	v_exp_f32_e32 v146, v49
	v_exp_f32_e32 v147, v53
	v_exp_f32_e32 v148, v57
	v_exp_f32_e32 v149, v61
	v_mul_f32_e32 v41, 0xbfb8aa3b, v91
	v_mul_f32_e32 v43, 0xbfb8aa3b, v123
	v_mul_f32_e32 v49, 0xbfb8aa3b, v125
	v_mul_f32_e32 v53, 0xbfb8aa3b, v93
	v_mul_f32_e32 v57, 0xbfb8aa3b, v127
	v_mul_f32_e32 v61, 0xbfb8aa3b, v129
	v_and_b32_e32 v96, 0xffff0000, v99
	v_lshlrev_b32_e32 v97, 16, v99
	v_and_b32_e32 v98, 0xffff0000, v100
	v_lshlrev_b32_e32 v99, 16, v100
	v_exp_f32_e32 v151, v37
	v_exp_f32_e32 v153, v39
	v_mul_f32_e32 v37, 0xbfb8aa3b, v94
	v_mul_f32_e32 v39, 0xbfb8aa3b, v95
	v_and_b32_e32 v100, 0xffff0000, v101
	v_exp_f32_e32 v155, v41
	v_exp_f32_e32 v157, v43
	v_exp_f32_e32 v158, v49
	v_exp_f32_e32 v159, v53
	v_exp_f32_e32 v160, v57
	v_exp_f32_e32 v161, v61
	v_mul_f32_e32 v41, 0xbfb8aa3b, v97
	v_mul_f32_e32 v43, 0xbfb8aa3b, v96
	v_mul_f32_e32 v49, 0xbfb8aa3b, v99
	v_mul_f32_e32 v53, 0xbfb8aa3b, v98
	s_waitcnt vmcnt(4)
	v_lshlrev_b32_e32 v130, 16, v102
	v_and_b32_e32 v102, 0xffff0000, v102
	v_lshlrev_b32_e32 v132, 16, v103
	v_exp_f32_e32 v162, v37
	v_exp_f32_e32 v163, v39
	v_lshlrev_b32_e32 v101, 16, v101
	v_mul_f32_e32 v61, 0xbfb8aa3b, v100
	v_and_b32_e32 v134, 0xffff0000, v103
	v_lshlrev_b32_e32 v136, 16, v104
	v_and_b32_e32 v104, 0xffff0000, v104
	v_lshlrev_b32_e32 v138, 16, v105
	v_and_b32_e32 v140, 0xffff0000, v105
	v_exp_f32_e32 v164, v41
	v_exp_f32_e32 v165, v43
	v_exp_f32_e32 v166, v49
	v_exp_f32_e32 v167, v53
	v_mul_f32_e32 v133, 0xbfb8aa3b, v102
	v_mul_f32_e32 v135, 0xbfb8aa3b, v132
	v_mul_f32_e32 v57, 0xbfb8aa3b, v101
	v_exp_f32_e32 v169, v61
	v_mul_f32_e32 v105, 0xbfb8aa3b, v130
	v_mul_f32_e32 v137, 0xbfb8aa3b, v134
	v_mul_f32_e32 v139, 0xbfb8aa3b, v136
	v_mul_f32_e32 v141, 0xbfb8aa3b, v104
	v_mul_f32_e32 v150, 0xbfb8aa3b, v138
	v_mul_f32_e32 v152, 0xbfb8aa3b, v140
	s_waitcnt vmcnt(1)
	v_lshlrev_b32_e32 v131, 16, v114
	v_and_b32_e32 v103, 0xffff0000, v114
	v_exp_f32_e32 v171, v133
	v_lshlrev_b32_e32 v133, 16, v115
	v_exp_f32_e32 v172, v135
	v_and_b32_e32 v135, 0xffff0000, v115
	v_add_f32_e32 v143, 1.0, v143
	v_add_f32_e32 v145, 1.0, v145
	v_exp_f32_e32 v168, v57
	v_exp_f32_e32 v170, v105
	v_exp_f32_e32 v173, v137
	v_lshlrev_b32_e32 v137, 16, v116
	v_exp_f32_e32 v174, v139
	v_and_b32_e32 v105, 0xffff0000, v116
	v_exp_f32_e32 v175, v141
	v_lshlrev_b32_e32 v139, 16, v117
	v_exp_f32_e32 v176, v150
	v_and_b32_e32 v141, 0xffff0000, v117
	v_exp_f32_e32 v177, v152
	v_add_f32_e32 v142, 1.0, v142
	v_add_f32_e32 v150, 1.0, v144
	v_add_f32_e32 v152, 1.0, v146
	v_add_f32_e32 v147, 1.0, v147
	v_add_f32_e32 v154, 1.0, v148
	v_add_f32_e32 v149, 1.0, v149
	v_mul_f32_e32 v178, 0xbfb8aa3b, v131
	v_mul_f32_e32 v179, 0xbfb8aa3b, v103
	v_mul_f32_e32 v180, 0xbfb8aa3b, v133
	v_mul_f32_e32 v181, 0xbfb8aa3b, v135
	s_waitcnt vmcnt(0)
	v_lshlrev_b32_e32 v114, 16, v118
	v_and_b32_e32 v115, 0xffff0000, v118
	v_and_b32_e32 v116, 0xffff0000, v119
	v_lshlrev_b32_e32 v117, 16, v119
	v_and_b32_e32 v118, 0xffff0000, v120
	v_lshlrev_b32_e32 v119, 16, v120
	v_rcp_f32_e32 v144, v143
	v_rcp_f32_e32 v148, v145
	v_add_f32_e32 v143, 1.0, v151
	v_add_f32_e32 v145, 1.0, v153
	v_mul_f32_e32 v183, 0xbfb8aa3b, v105
	v_mul_f32_e32 v187, 0xbfb8aa3b, v141
	v_rcp_f32_e32 v142, v142
	v_rcp_f32_e32 v146, v150
	v_rcp_f32_e32 v150, v152
	v_rcp_f32_e32 v152, v147
	v_rcp_f32_e32 v156, v149
	v_add_f32_e32 v147, 1.0, v155
	v_add_f32_e32 v149, 1.0, v157
	v_add_f32_e32 v151, 1.0, v158
	v_add_f32_e32 v153, 1.0, v159
	v_add_f32_e32 v155, 1.0, v160
	v_add_f32_e32 v157, 1.0, v161
	v_exp_f32_e32 v188, v178
	v_exp_f32_e32 v179, v179
	v_exp_f32_e32 v189, v180
	v_exp_f32_e32 v181, v181
	v_mul_f32_e32 v158, 0xbfb8aa3b, v114
	v_mul_f32_e32 v159, 0xbfb8aa3b, v115
	v_mul_f32_e32 v160, 0xbfb8aa3b, v117
	v_mul_f32_e32 v161, 0xbfb8aa3b, v116
	v_mul_f32_e32 v178, 0xbfb8aa3b, v119
	v_mul_f32_e32 v180, 0xbfb8aa3b, v118
	v_rcp_f32_e32 v143, v143
	v_rcp_f32_e32 v145, v145
	v_add_f32_e32 v162, 1.0, v162
	v_add_f32_e32 v163, 1.0, v163
	v_and_b32_e32 v120, 0xffff0000, v121
	v_lshlrev_b32_e32 v121, 16, v121
	v_exp_f32_e32 v183, v183
	v_exp_f32_e32 v187, v187
	v_rcp_f32_e32 v147, v147
	v_rcp_f32_e32 v149, v149
	v_add_f32_e32 v164, 1.0, v164
	v_add_f32_e32 v165, 1.0, v165
	v_add_f32_e32 v166, 1.0, v166
	v_add_f32_e32 v167, 1.0, v167
	v_exp_f32_e32 v192, v158
	v_exp_f32_e32 v193, v159
	v_exp_f32_e32 v194, v160
	v_exp_f32_e32 v195, v161
	v_exp_f32_e32 v196, v178
	v_exp_f32_e32 v197, v180
	v_rcp_f32_e32 v158, v162
	v_rcp_f32_e32 v159, v163
	v_mul_f32_e32 v190, 0xbfb8aa3b, v121
	v_mul_f32_e32 v191, 0xbfb8aa3b, v120
	v_add_f32_e32 v169, 1.0, v169
	v_rcp_f32_e32 v161, v164
	v_rcp_f32_e32 v160, v165
	v_rcp_f32_e32 v163, v166
	v_rcp_f32_e32 v162, v167
	v_rcp_f32_e32 v153, v153
	v_add_f32_e32 v168, 1.0, v168
	v_exp_f32_e32 v190, v190
	v_exp_f32_e32 v191, v191
	v_rcp_f32_e32 v164, v169
	v_add_f32_e32 v167, 1.0, v171
	v_add_f32_e32 v169, 1.0, v172
	v_add_f32_e32 v171, 1.0, v173
	v_add_f32_e32 v173, 1.0, v174
	v_mul_f32_e32 v182, 0xbfb8aa3b, v137
	v_rcp_f32_e32 v151, v151
	v_rcp_f32_e32 v165, v168
	v_add_f32_e32 v166, 1.0, v170
	v_add_f32_e32 v177, 1.0, v177
	v_rcp_f32_e32 v168, v167
	v_rcp_f32_e32 v170, v169
	v_rcp_f32_e32 v174, v173
	v_add_f32_e32 v167, 1.0, v188
	v_add_f32_e32 v169, 1.0, v179
	v_add_f32_e32 v173, 1.0, v181
	v_pk_mul_f32 v[86:87], v[142:143], v[86:87]
	v_pk_mul_f32 v[88:89], v[144:145], v[88:89]
	v_exp_f32_e32 v182, v182
	v_add_f32_e32 v175, 1.0, v175
	v_rcp_f32_e32 v166, v166
	v_rcp_f32_e32 v172, v171
	v_rcp_f32_e32 v180, v177
	v_add_f32_e32 v171, 1.0, v189
	v_add_f32_e32 v177, 1.0, v183
	v_add_f32_e32 v181, 1.0, v187
	v_pk_mul_f32 v[90:91], v[146:147], v[90:91]
	v_pk_mul_f32 v[122:123], v[148:149], v[122:123]
	v_rcp_f32_e32 v167, v167
	v_rcp_f32_e32 v169, v169
	v_rcp_f32_e32 v173, v173
	v_add_f32_e32 v142, 1.0, v192
	v_add_f32_e32 v143, 1.0, v193
	v_add_f32_e32 v144, 1.0, v194
	v_add_f32_e32 v145, 1.0, v195
	v_add_f32_e32 v146, 1.0, v196
	v_add_f32_e32 v147, 1.0, v197
	v_pk_mul_f32 v[64:65], v[86:87], v[64:65]
	v_pk_mul_f32 v[66:67], v[88:89], v[66:67]
	v_pk_mul_f32 v[86:87], v[158:159], v[94:95]
	v_rcp_f32_e32 v154, v154
	v_rcp_f32_e32 v155, v155
	v_add_f32_e32 v178, 1.0, v176
	v_rcp_f32_e32 v176, v175
	v_rcp_f32_e32 v171, v171
	v_rcp_f32_e32 v177, v177
	v_rcp_f32_e32 v181, v181
	v_pk_mul_f32 v[68:69], v[90:91], v[68:69]
	v_pk_mul_f32 v[70:71], v[122:123], v[70:71]
	v_pk_mul_f32 v[88:89], v[160:161], v[96:97]
	v_pk_mul_f32 v[90:91], v[162:163], v[98:99]
	v_rcp_f32_e32 v94, v142
	v_rcp_f32_e32 v95, v143
	v_rcp_f32_e32 v97, v144
	v_rcp_f32_e32 v96, v145
	v_rcp_f32_e32 v99, v146
	v_rcp_f32_e32 v98, v147
	v_pk_mul_f32 v[122:123], v[66:67], v[66:67]
	v_pk_mul_f32 v[86:87], v[86:87], v[50:51]
	v_rcp_f32_e32 v157, v157
	v_pk_mul_f32 v[92:93], v[152:153], v[92:93]
	v_add_f32_e32 v148, 1.0, v190
	v_add_f32_e32 v149, 1.0, v191
	v_pk_mul_f32 v[88:89], v[88:89], v[54:55]
	v_pk_fma_f32 v[50:51], v[64:65], v[64:65], v[122:123]
	v_pk_mul_f32 v[54:55], v[86:87], v[86:87]
	v_pk_mul_f32 v[124:125], v[150:151], v[124:125]
	v_pk_mul_f32 v[74:75], v[92:93], v[74:75]
	v_pk_mul_f32 v[92:93], v[164:165], v[100:101]
	v_rcp_f32_e32 v101, v148
	v_rcp_f32_e32 v100, v149
	v_pk_mul_f32 v[122:123], v[88:89], v[88:89]
	v_pk_fma_f32 v[50:51], v[68:69], v[68:69], v[50:51]
	v_add_f32_e32 v142, v54, v55
	v_lshlrev_b32_e32 v49, 16, v106
	v_and_b32_e32 v37, 0xffff0000, v106
	v_and_b32_e32 v39, 0xffff0000, v107
	v_add_f32_e32 v175, 1.0, v182
	v_pk_mul_f32 v[72:73], v[124:125], v[72:73]
	v_pk_mul_f32 v[90:91], v[90:91], v[58:59]
	v_pk_mul_f32 v[54:55], v[166:167], v[130:131]
	v_pk_mul_f32 v[58:59], v[168:169], v[102:103]
	v_pk_mul_f32 v[102:103], v[172:173], v[134:135]
	v_pk_fma_f32 v[134:135], v[70:71], v[70:71], v[50:51]
	v_add_f32_e32 v123, v123, v142
	v_lshlrev_b32_e32 v53, 16, v107
	v_lshlrev_b32_e32 v57, 16, v108
	v_and_b32_e32 v41, 0xffff0000, v108
	v_lshlrev_b32_e32 v61, 16, v109
	v_and_b32_e32 v43, 0xffff0000, v109
	v_lshlrev_b32_e32 v106, 16, v110
	v_and_b32_e32 v107, 0xffff0000, v110
	v_and_b32_e32 v108, 0xffff0000, v111
	v_lshlrev_b32_e32 v109, 16, v111
	v_and_b32_e32 v110, 0xffff0000, v112
	v_lshlrev_b32_e32 v111, 16, v112
	v_pk_mul_f32 v[126:127], v[154:155], v[126:127]
	v_rcp_f32_e32 v175, v175
	v_pk_mul_f32 v[92:93], v[92:93], v[62:63]
	v_pk_mul_f32 v[124:125], v[90:91], v[90:91]
	v_pk_mul_f32 v[62:63], v[170:171], v[132:133]
	v_pk_mul_f32 v[104:105], v[176:177], v[104:105]
	v_pk_mul_f32 v[132:133], v[180:181], v[140:141]
	v_pk_mul_f32 v[48:49], v[54:55], v[48:49]
	v_pk_mul_f32 v[50:51], v[58:59], v[36:37]
	v_pk_mul_f32 v[54:55], v[102:103], v[38:39]
	v_pk_mul_f32 v[36:37], v[94:95], v[114:115]
	v_pk_mul_f32 v[38:39], v[96:97], v[116:117]
	v_pk_mul_f32 v[94:95], v[98:99], v[118:119]
	v_pk_fma_f32 v[98:99], v[72:73], v[72:73], v[134:135]
	v_add_f32_e32 v102, v122, v123
	v_pk_mul_f32 v[128:129], v[156:157], v[128:129]
	v_pk_mul_f32 v[76:77], v[126:127], v[76:77]
	v_pk_mul_f32 v[52:53], v[62:63], v[52:53]
	v_pk_mul_f32 v[58:59], v[104:105], v[40:41]
	v_pk_mul_f32 v[62:63], v[132:133], v[42:43]
	v_pk_mul_f32 v[42:43], v[36:37], v[106:107]
	v_pk_mul_f32 v[40:41], v[38:39], v[108:109]
	v_pk_mul_f32 v[38:39], v[94:95], v[110:111]
	v_pk_fma_f32 v[94:95], v[74:75], v[74:75], v[98:99]
	v_add_f32_e32 v106, v125, v102
	v_and_b32_e32 v112, 0xffff0000, v113
	v_lshlrev_b32_e32 v113, 16, v113
	v_pk_mul_f32 v[78:79], v[128:129], v[78:79]
	v_pk_mul_f32 v[126:127], v[92:93], v[92:93]
	v_pk_mul_f32 v[96:97], v[100:101], v[120:121]
	v_pk_mul_f32 v[100:101], v[50:51], v[50:51]
	v_pk_mul_f32 v[98:99], v[42:43], v[42:43]
	v_pk_fma_f32 v[94:95], v[76:77], v[76:77], v[94:95]
	v_add_f32_e32 v106, v124, v106
	v_pk_mul_f32 v[36:37], v[96:97], v[112:113]
	v_pk_fma_f32 v[96:97], v[48:49], v[48:49], v[100:101]
	v_pk_mul_f32 v[100:101], v[40:41], v[40:41]
	v_add_f32_e32 v98, v98, v99
	v_pk_fma_f32 v[94:95], v[78:79], v[78:79], v[94:95]
	v_add_f32_e32 v112, v127, v106
	v_pk_mul_f32 v[128:129], v[174:175], v[136:137]
	v_pk_fma_f32 v[96:97], v[52:53], v[52:53], v[96:97]
	v_add_f32_e32 v101, v101, v98
	v_cndmask_b32_e64 v99, 0, v94, s[4:5]
	v_cndmask_b32_e64 v107, 0, v95, s[10:11]
	v_cndmask_b32_e64 v106, 0, v95, s[12:13]
	v_cndmask_b32_e64 v98, 0, v94, s[14:15]
	v_add_f32_e32 v112, v126, v112
	v_pk_mul_f32 v[56:57], v[128:129], v[56:57]
	v_pk_mul_f32 v[102:103], v[38:39], v[38:39]
	v_pk_fma_f32 v[96:97], v[54:55], v[54:55], v[96:97]
	v_cndmask_b32_e64 v109, 0, v94, s[0:1]
	v_cndmask_b32_e64 v108, 0, v94, s[2:3]
	v_cndmask_b32_e64 v111, 0, v95, s[6:7]
	v_cndmask_b32_e64 v110, 0, v95, s[8:9]
	v_add_f32_e32 v113, v100, v101
	v_pk_add_f32 v[98:99], v[98:99], v[106:107]
	v_cndmask_b32_e64 v107, 0, v112, s[20:21]
	v_cndmask_b32_e64 v106, 0, v112, s[22:23]
	v_pk_fma_f32 v[94:95], v[56:57], v[56:57], v[96:97]
	v_pk_add_f32 v[96:97], v[108:109], v[110:111]
	v_cndmask_b32_e64 v101, 0, v112, s[16:17]
	v_cndmask_b32_e64 v100, 0, v112, s[18:19]
	v_add_f32_e32 v103, v103, v113
	v_pk_add_f32 v[98:99], v[98:99], v[106:107]
	v_pk_add_f32 v[96:97], v[96:97], v[100:101]
	v_add_f32_e32 v106, v102, v103
	ds_bpermute_b32 v103, v80, v99
	ds_bpermute_b32 v102, v80, v98
	ds_bpermute_b32 v101, v80, v97
	ds_bpermute_b32 v100, v80, v96
	v_mul_f32_e32 v186, 0xbfb8aa3b, v139
	v_exp_f32_e32 v186, v186
	s_waitcnt lgkmcnt(2)
	v_pk_add_f32 v[98:99], v[98:99], v[102:103]
	ds_bpermute_b32 v103, v81, v99
	s_waitcnt lgkmcnt(1)
	v_pk_add_f32 v[96:97], v[96:97], v[100:101]
	ds_bpermute_b32 v102, v81, v98
	ds_bpermute_b32 v101, v81, v97
	ds_bpermute_b32 v100, v81, v96
	v_add_f32_e32 v179, 1.0, v186
	v_rcp_f32_e32 v178, v178
	s_waitcnt lgkmcnt(2)
	v_pk_add_f32 v[98:99], v[98:99], v[102:103]
	ds_bpermute_b32 v103, v82, v99
	s_waitcnt lgkmcnt(1)
	v_pk_add_f32 v[96:97], v[96:97], v[100:101]
	ds_bpermute_b32 v102, v82, v98
	ds_bpermute_b32 v101, v82, v97
	ds_bpermute_b32 v100, v82, v96
	v_rcp_f32_e32 v179, v179
	v_pk_fma_f32 v[94:95], v[58:59], v[58:59], v[94:95]
	s_waitcnt lgkmcnt(2)
	v_pk_add_f32 v[98:99], v[98:99], v[102:103]
	ds_bpermute_b32 v103, v83, v99
	s_waitcnt lgkmcnt(1)
	v_pk_add_f32 v[96:97], v[96:97], v[100:101]
	ds_bpermute_b32 v102, v83, v98
	ds_bpermute_b32 v101, v83, v97
	ds_bpermute_b32 v100, v83, v96
	v_pk_mul_f32 v[130:131], v[178:179], v[138:139]
	v_pk_mul_f32 v[104:105], v[36:37], v[36:37]
	s_waitcnt lgkmcnt(2)
	v_pk_add_f32 v[98:99], v[98:99], v[102:103]
	ds_bpermute_b32 v103, v84, v99
	s_waitcnt lgkmcnt(1)
	v_pk_add_f32 v[96:97], v[96:97], v[100:101]
	ds_bpermute_b32 v102, v84, v98
	ds_bpermute_b32 v101, v84, v97
	ds_bpermute_b32 v100, v84, v96
	v_pk_mul_f32 v[60:61], v[130:131], v[60:61]
	v_add_f32_e32 v105, v105, v106
	s_waitcnt lgkmcnt(2)
	v_pk_add_f32 v[98:99], v[98:99], v[102:103]
	ds_bpermute_b32 v103, v85, v99
	s_waitcnt lgkmcnt(1)
	v_pk_add_f32 v[96:97], v[96:97], v[100:101]
	ds_bpermute_b32 v102, v85, v98
	ds_bpermute_b32 v101, v85, v97
	ds_bpermute_b32 v100, v85, v96
	v_pk_fma_f32 v[94:95], v[60:61], v[60:61], v[94:95]
	v_add_f32_e32 v104, v104, v105
	s_waitcnt lgkmcnt(2)
	v_pk_add_f32 v[98:99], v[98:99], v[102:103]
	v_pk_fma_f32 v[94:95], v[62:63], v[62:63], v[94:95]
	s_waitcnt lgkmcnt(0)
	v_pk_add_f32 v[96:97], v[96:97], v[100:101]
	v_pk_fma_f32 v[98:99], v[98:99], s[46:47], v[26:27] op_sel_hi:[1,0,0]
	v_pk_fma_f32 v[96:97], v[96:97], s[46:47], v[26:27] op_sel_hi:[1,0,0]
	v_mul_f32_e32 v102, 0x4b800000, v99
	v_mul_f32_e32 v103, 0x4b800000, v98
	v_cmp_gt_f32_e64 s[24:25], s31, v98
	v_cmp_gt_f32_e64 s[26:27], s31, v99
	v_mul_f32_e32 v101, 0x4b800000, v96
	v_cmp_gt_f32_e32 vcc, s31, v96
	v_cndmask_b32_e64 v99, v99, v102, s[26:27]
	v_cndmask_b32_e64 v98, v98, v103, s[24:25]
	v_mul_f32_e32 v100, 0x4b800000, v97
	v_cmp_gt_f32_e64 s[28:29], s31, v97
	v_cndmask_b32_e32 v96, v96, v101, vcc
	v_rsq_f32_e32 v99, v99
	v_rsq_f32_e32 v98, v98
	v_cndmask_b32_e64 v97, v97, v100, s[28:29]
	v_rsq_f32_e32 v96, v96
	v_rsq_f32_e32 v97, v97
	v_mul_f32_e32 v102, 0x45800000, v99
	v_mul_f32_e32 v103, 0x45800000, v98
	v_mul_f32_e32 v101, 0x45800000, v96
	v_cndmask_b32_e64 v102, v99, v102, s[26:27]
	v_cndmask_b32_e64 v103, v98, v103, s[24:25]
	v_mul_f32_e32 v100, 0x45800000, v97
	v_cndmask_b32_e32 v101, v96, v101, vcc
	v_cndmask_b32_e64 v96, v103, v102, s[4:5]
	v_cndmask_b32_e64 v100, v97, v100, s[28:29]
	v_cndmask_b32_e64 v96, v96, v101, s[2:3]
	v_cndmask_b32_e64 v96, v96, v100, s[0:1]
	v_mul_f32_e32 v78, v78, v96
	v_mul_f32_e32 v64, v64, v96
	v_mul_f32_e32 v66, v66, v96
	v_mul_f32_e32 v68, v68, v96
	v_mul_f32_e32 v70, v70, v96
	v_mul_f32_e32 v72, v72, v96
	v_mul_f32_e32 v74, v74, v96
	v_mul_f32_e32 v76, v76, v96
	v_mul_f32_e32 v3, v207, v78
	v_mul_f32_e32 v4, v200, v64
	v_mul_f32_e32 v5, v201, v66
	v_mul_f32_e32 v6, v202, v68
	v_mul_f32_e32 v7, v203, v70
	v_mul_f32_e32 v64, v204, v72
	v_mul_f32_e32 v66, v205, v74
	v_mul_f32_e32 v68, v206, v76
	v_cvt_pk_bf16_f32 v0, v4, v5
	v_cvt_pk_bf16_f32 v1, v6, v7
	v_cvt_pk_bf16_f32 v2, v64, v66
	v_cvt_pk_bf16_f32 v3, v68, v3
	global_store_dwordx4 v[44:45], v[0:3], off offset:1024
	v_cndmask_b32_e64 v64, v103, v102, s[10:11]
	v_cndmask_b32_e64 v64, v64, v101, s[8:9]
	v_cndmask_b32_e64 v64, v64, v100, s[6:7]
	v_mul_f32_e32 v65, v65, v64
	v_mul_f32_e32 v66, v67, v64
	v_mul_f32_e32 v67, v69, v64
	v_mul_f32_e32 v68, v71, v64
	v_mul_f32_e32 v69, v73, v64
	v_mul_f32_e32 v70, v75, v64
	v_mul_f32_e32 v71, v77, v64
	v_mul_f32_e32 v64, v79, v64
	v_cndmask_b32_e64 v107, 0, v94, s[4:5]
	v_cndmask_b32_e64 v109, 0, v95, s[10:11]
	v_cndmask_b32_e64 v108, 0, v95, s[12:13]
	v_cndmask_b32_e64 v106, 0, v94, s[14:15]
	v_cndmask_b32_e64 v111, 0, v94, s[0:1]
	v_cndmask_b32_e64 v110, 0, v94, s[2:3]
	v_cndmask_b32_e64 v113, 0, v95, s[6:7]
	v_cndmask_b32_e64 v112, 0, v95, s[8:9]
	v_pk_add_f32 v[94:95], v[110:111], v[112:113]
	v_cndmask_b32_e64 v45, 0, v104, s[16:17]
	v_cndmask_b32_e64 v44, 0, v104, s[18:19]
	v_pk_add_f32 v[96:97], v[106:107], v[108:109]
	v_cndmask_b32_e64 v99, 0, v104, s[20:21]
	v_cndmask_b32_e64 v98, 0, v104, s[22:23]
	v_pk_add_f32 v[44:45], v[94:95], v[44:45]
	v_pk_add_f32 v[94:95], v[96:97], v[98:99]
	ds_bpermute_b32 v99, v80, v95
	ds_bpermute_b32 v98, v80, v94
	ds_bpermute_b32 v97, v80, v45
	ds_bpermute_b32 v96, v80, v44
	s_waitcnt lgkmcnt(2)
	v_pk_add_f32 v[94:95], v[94:95], v[98:99]
	s_waitcnt lgkmcnt(0)
	v_pk_add_f32 v[44:45], v[44:45], v[96:97]
	ds_bpermute_b32 v97, v81, v45
	ds_bpermute_b32 v96, v81, v44
	s_waitcnt lgkmcnt(0)
	v_pk_add_f32 v[44:45], v[44:45], v[96:97]
	v_mul_f32_e32 v0, v208, v65
	v_mul_f32_e32 v1, v209, v66
	v_mul_f32_e32 v2, v210, v67
	v_mul_f32_e32 v3, v211, v68
	v_mul_f32_e32 v4, v212, v69
	v_mul_f32_e32 v5, v213, v70
	v_mul_f32_e32 v6, v214, v71
	v_mul_f32_e32 v7, v215, v64
	v_cvt_pk_bf16_f32 v0, v0, v1
	v_cvt_pk_bf16_f32 v1, v2, v3
	v_cvt_pk_bf16_f32 v2, v4, v5
	v_cvt_pk_bf16_f32 v3, v6, v7
	global_store_dwordx4 v[34:35], v[0:3], off offset:1024
	ds_bpermute_b32 v35, v81, v95
	ds_bpermute_b32 v34, v81, v94
	ds_bpermute_b32 v65, v82, v45
	ds_bpermute_b32 v64, v82, v44
	s_waitcnt lgkmcnt(2)
	v_pk_add_f32 v[34:35], v[94:95], v[34:35]
	ds_bpermute_b32 v67, v82, v35
	ds_bpermute_b32 v66, v82, v34
	s_waitcnt lgkmcnt(2)
	v_pk_add_f32 v[44:45], v[44:45], v[64:65]
	ds_bpermute_b32 v65, v83, v45
	ds_bpermute_b32 v64, v83, v44
	s_waitcnt lgkmcnt(2)
	v_pk_add_f32 v[34:35], v[34:35], v[66:67]
	ds_bpermute_b32 v67, v83, v35
	ds_bpermute_b32 v66, v83, v34
	s_waitcnt lgkmcnt(2)
	v_pk_add_f32 v[44:45], v[44:45], v[64:65]
	ds_bpermute_b32 v65, v84, v45
	ds_bpermute_b32 v64, v84, v44
	s_waitcnt lgkmcnt(2)
	v_pk_add_f32 v[34:35], v[34:35], v[66:67]
	v_cndmask_b32_e64 v66, v103, v102, s[20:21]
	v_cndmask_b32_e64 v66, v66, v101, s[18:19]
	v_cndmask_b32_e64 v66, v66, v100, s[16:17]
	v_mul_f32_e32 v68, v86, v66
	v_mul_f32_e32 v69, v87, v66
	v_mul_f32_e32 v70, v89, v66
	v_mul_f32_e32 v71, v88, v66
	v_mul_f32_e32 v72, v91, v66
	v_mul_f32_e32 v73, v90, v66
	v_mul_f32_e32 v74, v93, v66
	v_mul_f32_e32 v66, v92, v66
	ds_bpermute_b32 v67, v84, v35
	v_mul_f32_e32 v0, v68, v216
	v_mul_f32_e32 v1, v69, v217
	v_mul_f32_e32 v2, v70, v218
	v_mul_f32_e32 v3, v71, v219
	v_mul_f32_e32 v4, v72, v220
	v_mul_f32_e32 v5, v73, v221
	v_mul_f32_e32 v6, v74, v222
	v_mul_f32_e32 v7, v66, v223
	v_cvt_pk_bf16_f32 v0, v0, v1
	v_cvt_pk_bf16_f32 v1, v2, v3
	v_cvt_pk_bf16_f32 v2, v4, v5
	v_cvt_pk_bf16_f32 v3, v6, v7
	global_store_dwordx4 v[32:33], v[0:3], off offset:1024
	ds_bpermute_b32 v66, v84, v34
	s_waitcnt lgkmcnt(2)
	v_pk_add_f32 v[32:33], v[44:45], v[64:65]
	ds_bpermute_b32 v45, v85, v33
	ds_bpermute_b32 v44, v85, v32
	s_waitcnt lgkmcnt(2)
	v_pk_add_f32 v[34:35], v[34:35], v[66:67]
	ds_bpermute_b32 v65, v85, v35
	ds_bpermute_b32 v64, v85, v34
	s_waitcnt lgkmcnt(2)
	v_pk_add_f32 v[32:33], v[32:33], v[44:45]
	s_waitcnt lgkmcnt(0)
	v_pk_add_f32 v[34:35], v[34:35], v[64:65]
	s_nop 0
	v_pk_fma_f32 v[34:35], v[34:35], s[46:47], v[26:27] op_sel_hi:[1,0,0]
	v_pk_fma_f32 v[32:33], v[32:33], s[46:47], v[26:27] op_sel_hi:[1,0,0]
	v_mul_f32_e32 v64, 0x4b800000, v35
	v_mul_f32_e32 v65, 0x4b800000, v34
	v_cmp_gt_f32_e64 s[24:25], s31, v34
	v_cmp_gt_f32_e64 s[26:27], s31, v35
	v_mul_f32_e32 v44, 0x4b800000, v33
	v_mul_f32_e32 v45, 0x4b800000, v32
	v_cmp_gt_f32_e32 vcc, s31, v32
	v_cmp_gt_f32_e64 s[28:29], s31, v33
	v_cndmask_b32_e64 v35, v35, v64, s[26:27]
	v_cndmask_b32_e64 v34, v34, v65, s[24:25]
	v_cndmask_b32_e64 v33, v33, v44, s[28:29]
	v_cndmask_b32_e32 v32, v32, v45, vcc
	v_rsq_f32_e32 v35, v35
	v_rsq_f32_e32 v34, v34
	v_rsq_f32_e32 v33, v33
	v_rsq_f32_e32 v32, v32
	v_mul_f32_e32 v64, 0x45800000, v35
	v_mul_f32_e32 v65, 0x45800000, v34
	v_mul_f32_e32 v44, 0x45800000, v33
	v_mul_f32_e32 v45, 0x45800000, v32
	v_cndmask_b32_e64 v35, v35, v64, s[26:27]
	v_cndmask_b32_e64 v34, v34, v65, s[24:25]
	v_cndmask_b32_e64 v33, v33, v44, s[28:29]
	v_cndmask_b32_e32 v32, v32, v45, vcc
	v_cndmask_b32_e64 v44, v34, v35, s[4:5]
	v_cndmask_b32_e64 v44, v44, v32, s[2:3]
	v_cndmask_b32_e64 v44, v44, v33, s[0:1]
	v_mul_f32_e32 v45, v48, v44
	v_mul_f32_e32 v48, v50, v44
	v_mul_f32_e32 v50, v52, v44
	v_mul_f32_e32 v52, v54, v44
	v_mul_f32_e32 v54, v56, v44
	v_mul_f32_e32 v56, v58, v44
	v_mul_f32_e32 v58, v60, v44
	v_mul_f32_e32 v44, v62, v44
	v_add_co_u32_e32 v30, vcc, s39, v30
	v_mul_f32_e32 v0, v200, v45
	v_mul_f32_e32 v1, v201, v48
	v_mul_f32_e32 v2, v202, v50
	v_mul_f32_e32 v3, v203, v52
	v_mul_f32_e32 v4, v204, v54
	v_mul_f32_e32 v5, v205, v56
	v_mul_f32_e32 v6, v206, v58
	v_mul_f32_e32 v7, v207, v44
	v_cvt_pk_bf16_f32 v0, v0, v1
	v_cvt_pk_bf16_f32 v1, v2, v3
	v_cvt_pk_bf16_f32 v2, v4, v5
	v_cvt_pk_bf16_f32 v3, v6, v7
	global_store_dwordx4 v[46:47], v[0:3], off offset:1024
	v_cndmask_b32_e64 v44, v34, v35, s[10:11]
	v_cndmask_b32_e64 v44, v44, v32, s[8:9]
	v_cndmask_b32_e64 v44, v44, v33, s[6:7]
	v_mul_f32_e32 v45, v49, v44
	v_mul_f32_e32 v46, v51, v44
	v_mul_f32_e32 v47, v53, v44
	v_mul_f32_e32 v48, v55, v44
	v_addc_co_u32_e32 v31, vcc, 0, v31, vcc
	v_mul_f32_e32 v49, v57, v44
	v_mul_f32_e32 v50, v59, v44
	v_mul_f32_e32 v51, v61, v44
	v_mul_f32_e32 v44, v63, v44
	v_add_co_u32_e32 v28, vcc, 0xee95000, v28
	v_mul_f32_e32 v0, v208, v45
	v_mul_f32_e32 v1, v209, v46
	v_mul_f32_e32 v2, v210, v47
	v_mul_f32_e32 v3, v211, v48
	v_mul_f32_e32 v4, v212, v49
	v_mul_f32_e32 v5, v213, v50
	v_mul_f32_e32 v6, v214, v51
	v_mul_f32_e32 v7, v215, v44
	v_cvt_pk_bf16_f32 v0, v0, v1
	v_cvt_pk_bf16_f32 v1, v2, v3
	v_cvt_pk_bf16_f32 v2, v4, v5
	v_cvt_pk_bf16_f32 v3, v6, v7
	global_store_dwordx4 v[30:31], v[0:3], off offset:1024
	v_cndmask_b32_e64 v30, v34, v35, s[20:21]
	v_cndmask_b32_e64 v30, v30, v32, s[18:19]
	v_cndmask_b32_e64 v30, v30, v33, s[16:17]
	v_mul_f32_e32 v31, v42, v30
	v_mul_f32_e32 v32, v43, v30
	v_mul_f32_e32 v33, v41, v30
	v_mul_f32_e32 v34, v40, v30
	v_addc_co_u32_e32 v29, vcc, 0, v29, vcc
	v_mul_f32_e32 v35, v39, v30
	v_mul_f32_e32 v38, v38, v30
	v_mul_f32_e32 v37, v37, v30
	v_mul_f32_e32 v30, v36, v30
	v_mul_f32_e32 v0, v31, v216
	v_mul_f32_e32 v1, v32, v217
	v_mul_f32_e32 v2, v33, v218
	v_mul_f32_e32 v3, v34, v219
	v_mul_f32_e32 v4, v35, v220
	v_mul_f32_e32 v5, v38, v221
	v_mul_f32_e32 v6, v37, v222
	v_mul_f32_e32 v7, v30, v223
	v_cvt_pk_bf16_f32 v0, v0, v1
	v_cvt_pk_bf16_f32 v1, v2, v3
	v_cvt_pk_bf16_f32 v2, v4, v5
	v_cvt_pk_bf16_f32 v3, v6, v7
	global_store_dwordx4 v[28:29], v[0:3], off offset:1024
	s_cbranch_scc1 .LBB0_1543
